# stack: leader releases before own invalidate + counted wait in residual epilogue + static priority raise for waves 4-7 in attention
# speedup vs baseline: 1.0044x; 1.0044x over previous
; __device__ __forceinline__ void attn_phase(LAS unsigned char* lds, bf16* Qb, const bf16* Kb, const bf16* Vb, const float* rpb_l, int seq_len, int G, int bx, int tid, int wave, int lane) {
;     ...
;     ATT_PREFETCH();
.LBB0_89:
	s_load_dwordx2 s[8:9], s[96:97], 0x90
	s_add_i32 s7, s7, 1
	s_and_b64 s[4:5], exec, s[40:41]
	s_cselect_b32 s7, 3, s7
	s_ashr_i32 s3, s3, 8
	s_cbranch_scc0 .Lattn_prio_skip
	s_setprio 1
.Lattn_prio_skip:
	s_waitcnt lgkmcnt(0)
	s_add_u32 s10, s8, 0x4000000
	s_addc_u32 s11, s9, 0
	s_lshr_b32 s22, s80, 6
	s_and_b64 s[4:5], s[12:13], exec
	s_mul_i32 s17, s15, s0
	s_cselect_b32 s16, 5, 6
	s_add_i32 s4, s17, s6
	s_add_i32 s18, s22, -1
	s_ashr_i32 s5, s4, s16
	s_add_i32 s19, s16, 3
	s_and_b32 s62, s4, s18
	s_and_b32 s21, s5, 7
	s_ashr_i32 s15, s4, s19
	s_and_b64 s[4:5], s[12:13], exec
	v_sub_u32_e64 v0, s62, 4 clamp
	s_cselect_b32 s20, 11, 12
	s_add_i32 s22, s22, -8
	v_readfirstlane_b32 s4, v0
	s_min_u32 s23, s4, s22
	s_lshl_b32 s4, s21, 1
	v_lshrrev_b32_e32 v100, 4, v74
	s_add_i32 s12, s4, s3
	s_lshl_b32 s63, s15, s20
	v_lshl_or_b32 v8, s12, 3, v100
	v_lshrrev_b32_e64 v206, 12, s63
	v_lshlrev_b32_e32 v207, 7, v206
	v_sub_u32_e32 v207, v207, v206
	v_add_u32_e32 v8, v207, v8
	v_ashrrev_i32_e32 v9, 31, v8
	v_or_b32_e32 v10, s63, v98
	s_lshl_b32 s4, s62, 6
	v_lshl_add_u32 v10, s23, 6, v10
	v_lshlrev_b64 v[8:9], 16, v[8:9]
	s_add_i32 s4, s63, s4
	v_ashrrev_i32_e32 v11, 31, v10
	v_lshl_add_u64 v[8:9], s[10:11], 0, v[8:9]
	v_add_u32_e32 v0, s4, v99
	v_lshl_add_u64 v[8:9], v[10:11], 4, v[8:9]
	s_lshl_b32 s78, s14, 8
	v_ashrrev_i32_e32 v1, 31, v0
	v_lshl_add_u64 v[16:17], v[8:9], 0, s[78:79]
	s_lshl_b32 s4, s12, 6
	v_lshlrev_b64 v[0:1], 11, v[0:1]
	v_add_co_u32_e32 v24, vcc, s86, v16
	s_lshl_b32 s78, s7, 8
	s_ashr_i32 s5, s4, 31
	v_lshl_add_u64 v[0:1], s[8:9], 0, v[0:1]
	v_addc_co_u32_e32 v25, vcc, 0, v17, vcc
	v_lshl_add_u64 v[52:53], v[8:9], 0, s[78:79]
	v_lshl_add_u64 v[0:1], s[4:5], 1, v[0:1]
	v_and_b32_e32 v208, 48, v74
	v_add_co_u32_e32 v56, vcc, s86, v52
	v_lshl_add_u64 v[4:5], v[0:1], 0, v[208:209]
	s_nop 0
	v_addc_co_u32_e32 v57, vcc, 0, v53, vcc
	global_load_dwordx4 v[0:3], v[4:5], off
	s_nop 0
	global_load_dwordx4 v[4:7], v[4:5], off offset:64
	s_nop 0
	global_load_dwordx4 v[40:43], v[16:17], off
	global_load_dwordx4 v[8:11], v[16:17], off offset:1024
	global_load_dwordx4 v[44:47], v[24:25], off
	global_load_dwordx4 v[12:15], v[24:25], off offset:1024
	global_load_dwordx4 v[32:35], v[52:53], off
	global_load_dwordx4 v[20:23], v[52:53], off offset:1024
	global_load_dwordx4 v[28:31], v[56:57], off
	global_load_dwordx4 v[36:39], v[56:57], off offset:1024
	global_load_dwordx4 v[48:51], v[16:17], off offset:2048
	s_nop 0
	global_load_dwordx4 v[16:19], v[16:17], off offset:3072
	s_nop 0
	global_load_dwordx4 v[60:63], v[24:25], off offset:2048
	s_nop 0
	global_load_dwordx4 v[24:27], v[24:25], off offset:3072
	s_nop 0
	global_load_dwordx4 v[64:67], v[52:53], off offset:2048
	s_nop 0
	global_load_dwordx4 v[52:55], v[52:53], off offset:3072
	s_nop 0
	global_load_dwordx4 v[68:71], v[56:57], off offset:2048
	s_nop 0
	global_load_dwordx4 v[56:59], v[56:57], off offset:3072
	s_mul_i32 s4, s21, 0x3a2
	v_add_u32_e32 v72, s4, v188
	v_readlane_b32 s4, v255, 0
	v_ashrrev_i32_e32 v73, 31, v72
	v_readlane_b32 s5, v255, 1
	v_mov_b32_e32 v105, 0
	s_nop 0
	v_lshl_add_u64 v[72:73], v[72:73], 2, s[4:5]
	global_load_dword v75, v[72:73], off
	s_movk_i32 s4, 0x1a2
	v_cmp_gt_i32_e64 s[38:39], s4, v188
	s_and_saveexec_b64 s[12:13], s[38:39]
	s_cbranch_execz .LBB0_91
	global_load_dword v72, v[72:73], off offset:2048
	s_waitcnt vmcnt(0)
	v_mul_f32_e32 v105, 0x3fb8aa3b, v72

; __device__ __forceinline__ void attn_phase(LAS unsigned char* lds, bf16* Qb, const bf16* Kb, const bf16* Vb, const float* rpb_l, int seq_len, int G, int bx, int tid, int wave, int lane) {
;     ...
;     __syncthreads();
.LBB0_103:
	s_setprio 0
	s_waitcnt lgkmcnt(0)
	s_barrier

;     __device__ __forceinline__ void operator()(const f32x4 (&acc)[2][2][4][2], const Unit& u, int wr, int wc, int fr, int fq) const {
;     ...
;             if (b16) {
; #pragma unroll
;                 for (int m = 0; m < 4; ++m)
; #pragma unroll
;                     for (int bj = 0; bj < 2; ++bj) { const int c_ = col0 + bj * HALF;
;                         const u32x4 w = *(const u32x4*)((const char*)b16 + ((size_t)((u.pm * 2 + ai) * (ldc >> 6) + (c_ >> 6)) << 14) + lds_byte(wr * 64 + m * 16 + fr, c_ & 63));
;                         bs[m][bj][0] = (f32x4){__builtin_bit_cast(float, w.x << 16), __builtin_bit_cast(float, w.x & 0xffff0000u), __builtin_bit_cast(float, w.y << 16), __builtin_bit_cast(float, w.y & 0xffff0000u)};
;                         bs[m][bj][1] = (f32x4){__builtin_bit_cast(float, w.z << 16), __builtin_bit_cast(float, w.z & 0xffff0000u), __builtin_bit_cast(float, w.w << 16), __builtin_bit_cast(float, w.w & 0xffff0000u)}; }
.LBB0_237:
	s_lshl_b32 s4, s33, 8
	s_or_b32 s96, s4, s83
	v_or_b32_e32 v218, s96, v241
	s_bfe_u32 s4, s83, 0x10005
	v_lshlrev_b32_e32 v145, 1, v218
	v_mov_b32_e32 v144, s4
	v_and_b32_e32 v145, 48, v145
	v_cndmask_b32_e64 v146, 0, 1, s[24:25]
	v_cmp_ne_u32_e64 s[48:49], 1, v146
	v_lshlrev_b32_e64 v146, 10, s4
	v_bitop3_b32 v147, v145, v243, v242 bitop3:0x36
	v_or_b32_e32 v148, s71, v144
	v_or_b32_e32 v249, v145, v242
	v_or_b32_e32 v145, s0, v144
	v_or_b32_e32 v144, s1, v144
	s_mov_b64 s[44:45], -1
	s_andn2_b64 vcc, exec, s[24:25]
	v_or3_b32 v220, v147, v146, s82
	v_lshlrev_b32_e32 v252, 10, v148
	v_lshlrev_b32_e32 v251, 10, v145
	v_lshlrev_b32_e32 v250, 10, v144
	s_cbranch_vccnz .LBB0_239
	s_lshl_b32 s4, s93, 5
	s_ashr_i32 s5, s96, 6
	s_add_i32 s44, s5, s4
	v_bitop3_b32 v152, v249, v251, v243 bitop3:0xde
	s_add_i32 s6, s44, 2
	s_ashr_i32 s45, s44, 31
	v_ashrrev_i32_e32 v221, 31, v220
	v_bitop3_b32 v148, v249, v252, v243 bitop3:0xde
	v_ashrrev_i32_e32 v153, 31, v152
	v_bitop3_b32 v156, v249, v250, v243 bitop3:0xde
	s_ashr_i32 s7, s6, 31
	s_lshl_b64 s[46:47], s[44:45], 14
	v_lshl_add_u64 v[160:161], s[54:55], 0, v[220:221]
	v_ashrrev_i32_e32 v149, 31, v148
	v_lshl_add_u64 v[168:169], s[54:55], 0, v[152:153]
	v_ashrrev_i32_e32 v157, 31, v156
	s_lshl_b64 s[6:7], s[6:7], 14
	v_lshl_add_u64 v[144:145], v[160:161], 0, s[46:47]
	v_lshl_add_u64 v[164:165], s[54:55], 0, v[148:149]
	v_lshl_add_u64 v[152:153], v[168:169], 0, s[46:47]
	v_lshl_add_u64 v[170:171], s[54:55], 0, v[156:157]
	v_lshl_add_u64 v[160:161], v[160:161], 0, s[6:7]
	v_lshl_add_u64 v[168:169], v[168:169], 0, s[6:7]
	v_lshl_add_u64 v[148:149], v[164:165], 0, s[46:47]
	v_lshl_add_u64 v[156:157], v[170:171], 0, s[46:47]
	global_load_dwordx4 v[160:163], v[160:161], off
	v_lshl_add_u64 v[164:165], v[164:165], 0, s[6:7]
	global_load_dwordx4 v[222:225], v[168:169], off
	v_lshl_add_u64 v[168:169], v[170:171], 0, s[6:7]
	global_load_dwordx4 v[144:147], v[144:145], off
	s_lshl_b32 s97, s93, 8
	global_load_dwordx4 v[148:151], v[148:149], off
	s_mov_b64 s[44:45], 0
	global_load_dwordx4 v[152:155], v[152:153], off
	global_load_dwordx4 v[156:159], v[156:157], off
	global_load_dwordx4 v[164:167], v[164:165], off
	global_load_dwordx4 v[234:237], v[168:169], off
	s_waitcnt vmcnt(3)
	v_lshlrev_b32_e32 v204, 16, v144
	v_and_b32_e32 v205, 0xffff0000, v144
	v_lshlrev_b32_e32 v196, 16, v160
	v_and_b32_e32 v197, 0xffff0000, v160
	v_lshlrev_b32_e32 v198, 16, v161
	v_and_b32_e32 v199, 0xffff0000, v161
	v_lshlrev_b32_e32 v160, 16, v224
	v_and_b32_e32 v161, 0xffff0000, v224
	v_add_u32_e32 v224, s97, v240
	v_lshlrev_b32_e32 v206, 16, v145
	v_and_b32_e32 v207, 0xffff0000, v145
	v_lshlrev_b32_e32 v200, 16, v146
	v_and_b32_e32 v201, 0xffff0000, v146
	v_lshlrev_b32_e32 v202, 16, v147
	v_and_b32_e32 v203, 0xffff0000, v147
	v_lshlrev_b32_e32 v188, 16, v148
	v_and_b32_e32 v189, 0xffff0000, v148
	v_lshlrev_b32_e32 v190, 16, v149
	v_and_b32_e32 v191, 0xffff0000, v149
	v_lshlrev_b32_e32 v184, 16, v150
	v_and_b32_e32 v185, 0xffff0000, v150
	v_lshlrev_b32_e32 v186, 16, v151
	v_and_b32_e32 v187, 0xffff0000, v151
	v_lshlrev_b32_e32 v172, 16, v152
	v_and_b32_e32 v173, 0xffff0000, v152
	v_lshlrev_b32_e32 v174, 16, v153
	v_and_b32_e32 v175, 0xffff0000, v153
	v_lshlrev_b32_e32 v168, 16, v154
	v_and_b32_e32 v169, 0xffff0000, v154
	v_lshlrev_b32_e32 v170, 16, v155
	v_and_b32_e32 v171, 0xffff0000, v155
	v_lshlrev_b32_e32 v192, 16, v162
	v_and_b32_e32 v193, 0xffff0000, v162
	v_lshlrev_b32_e32 v194, 16, v163
	v_and_b32_e32 v195, 0xffff0000, v163
	v_lshlrev_b32_e32 v162, 16, v225
	v_and_b32_e32 v163, 0xffff0000, v225
	v_ashrrev_i32_e32 v225, 31, v224
	s_waitcnt vmcnt(2)
	v_lshlrev_b32_e32 v152, 16, v156
	v_and_b32_e32 v153, 0xffff0000, v156
	v_lshlrev_b32_e32 v154, 16, v157
	v_and_b32_e32 v155, 0xffff0000, v157
	s_waitcnt vmcnt(1)
	v_lshlrev_b32_e32 v180, 16, v164
	v_and_b32_e32 v181, 0xffff0000, v164
	v_lshlrev_b32_e32 v182, 16, v165
	v_and_b32_e32 v183, 0xffff0000, v165
	v_lshlrev_b32_e32 v176, 16, v166
	v_and_b32_e32 v177, 0xffff0000, v166
	v_lshlrev_b32_e32 v178, 16, v167
	v_and_b32_e32 v179, 0xffff0000, v167
	v_lshlrev_b32_e32 v164, 16, v222
	v_and_b32_e32 v165, 0xffff0000, v222
	v_lshlrev_b32_e32 v166, 16, v223
	v_and_b32_e32 v167, 0xffff0000, v223
	v_lshlrev_b32_e32 v156, 16, v158
	v_and_b32_e32 v157, 0xffff0000, v158
	v_lshlrev_b32_e32 v158, 16, v159
	v_and_b32_e32 v159, 0xffff0000, v159
	s_waitcnt vmcnt(0)
	v_lshlrev_b32_e32 v148, 16, v234
	v_and_b32_e32 v149, 0xffff0000, v234
	v_lshlrev_b32_e32 v150, 16, v235
	v_and_b32_e32 v151, 0xffff0000, v235
	v_lshlrev_b32_e32 v144, 16, v236
	v_and_b32_e32 v145, 0xffff0000, v236
	v_lshlrev_b32_e32 v146, 16, v237
	v_and_b32_e32 v147, 0xffff0000, v237
